# stick-breaking: unmasked copy also for the key-offset-0 quarter (non-meta tiles fully below the wave's rows)
# baseline (speedup 1.0000x reference)
; __device__ __forceinline__ void sb_unit(const Frame& F, int b, int hd, int qi, int dry) {
;     ...
;             float run = C;
;             if (!meta && key0 + 96 < tqw + 31) SB_HALF(96);
;             if (!meta && key0 + 64 < tqw + 31 && __any(run >= SB_DEAD)) SB_HALF(64);
;             if (!meta && key0 + 32 < tqw + 31 && __any(run >= SB_DEAD)) SB_HALF(32);
;             if (__any(run >= SB_DEAD)) SB_HALF(0);
.LBB0_347:
	v_cmp_le_f32_e32 vcc, s22, v125
	s_cbranch_vccz .LBB0_349
	s_and_b64 vcc, exec, s[18:19]
	s_cbranch_vccnz .Lsbq0_masked_2
	s_add_i32 s61, s35, 32
	s_cmp_le_i32 s61, s26
	s_cbranch_scc1 .Lsbq0_nomask_2
.Lsbq0_masked_2:
	ds_read_b128 v[32:35], v129
	ds_read_b128 v[214:217], v129 offset:32
	ds_read_b128 v[210:213], v129 offset:64
	ds_read_b128 v[130:133], v129 offset:96
	ds_read_b64_tr_b16 v[92:93], v128 offset:36864
	ds_read_b64_tr_b16 v[94:95], v128 offset:38400
	ds_read_b64_tr_b16 v[90:91], v128 offset:38464
	ds_read_b64_tr_b16 v[88:89], v128 offset:36928
	ds_read_b64_tr_b16 v[84:85], v128 offset:39936
	ds_read_b64_tr_b16 v[86:87], v128 offset:41472
	ds_read_b64_tr_b16 v[82:83], v128 offset:41536
	ds_read_b64_tr_b16 v[80:81], v128 offset:40000
	v_cndmask_b32_e64 v129, v114, 16, s[18:19]
	v_sub_u32_e32 v127, v129, v127
	v_cmp_lt_i32_e32 vcc, 0, v127
	v_cmp_lt_i32_e64 s[0:1], 27, v127
	v_exp_f32_e32 v128, v125
	s_waitcnt lgkmcnt(11)
	v_mfma_f32_32x32x16_bf16 v[32:47], v[32:35], v[48:51], 0
	s_waitcnt lgkmcnt(10)
	v_mfma_f32_32x32x16_bf16 v[32:47], v[214:217], v[52:55], v[32:47]
	s_waitcnt lgkmcnt(9)
	v_mfma_f32_32x32x16_bf16 v[32:47], v[210:213], v[56:59], v[32:47]
	s_waitcnt lgkmcnt(8)
	v_mfma_f32_32x32x16_bf16 v[32:47], v[130:133], v[60:63], v[32:47]
	s_nop 11
	v_min_f32_e64 v32, -v32, s60
	v_min_f32_e64 v33, -v33, s60
	v_exp_f32_e32 v32, v32
	v_min_f32_e64 v34, -v34, s60
	v_exp_f32_e32 v33, v33
	v_exp_f32_e32 v34, v34
	v_min_f32_e64 v35, -v35, s60
	v_exp_f32_e32 v130, v35
	v_add_f32_e32 v35, 1.0, v32
	v_add_f32_e32 v129, 1.0, v33
	v_rcp_f32_e32 v35, v35
	v_add_f32_e32 v131, 1.0, v34
	v_rcp_f32_e32 v129, v129
	v_rcp_f32_e32 v131, v131
	v_add_f32_e32 v132, 1.0, v130
	v_rcp_f32_e32 v132, v132
	v_mul_f32_e32 v32, v32, v35
	v_mul_f32_e32 v133, v128, v35
	v_min_f32_e64 v36, -v36, s60
	v_mul_f32_e32 v33, v33, v129
	v_mul_f32_e32 v134, v128, v129
	v_cndmask_b32_e32 v35, 1.0, v32, vcc
	v_cndmask_b32_e32 v133, 0, v133, vcc
	v_cmp_lt_i32_e32 vcc, 1, v127
	v_mul_f32_e32 v34, v34, v131
	v_exp_f32_e32 v32, v36
	v_cndmask_b32_e32 v129, 1.0, v33, vcc
	v_cndmask_b32_e32 v134, 0, v134, vcc
	v_cmp_lt_i32_e32 vcc, 2, v127
	v_add_f32_e32 v36, 1.0, v32
	v_rcp_f32_e32 v36, v36
	v_cndmask_b32_e32 v33, 1.0, v34, vcc
	v_mul_f32_e32 v34, v128, v131
	v_cndmask_b32_e32 v135, 0, v34, vcc
	v_mul_f32_e32 v34, v130, v132
	v_cmp_lt_i32_e32 vcc, 3, v127
	v_mul_f32_e32 v32, v32, v36
	v_mul_f32_e32 v36, v128, v36
	v_cndmask_b32_e32 v131, 1.0, v34, vcc
	v_mul_f32_e32 v34, v128, v132
	v_cndmask_b32_e32 v132, 0, v34, vcc
	v_min_f32_e64 v34, -v37, s60
	v_exp_f32_e32 v34, v34
	v_cmp_lt_i32_e32 vcc, 8, v127
	v_min_f32_e64 v37, -v38, s60
	v_cndmask_b32_e32 v136, 0, v36, vcc
	v_add_f32_e32 v36, 1.0, v34
	v_rcp_f32_e32 v36, v36
	v_exp_f32_e32 v37, v37
	v_cndmask_b32_e32 v32, 1.0, v32, vcc
	v_cmp_lt_i32_e32 vcc, 9, v127
	v_mul_f32_e32 v34, v34, v36
	v_cndmask_b32_e32 v38, 1.0, v34, vcc
	v_add_f32_e32 v34, 1.0, v37
	v_min_f32_e64 v39, -v39, s60
	v_rcp_f32_e32 v34, v34
	v_exp_f32_e32 v39, v39
	v_mul_f32_e32 v36, v128, v36
	v_cndmask_b32_e32 v137, 0, v36, vcc
	v_mul_f32_e32 v36, v37, v34
	v_add_f32_e32 v37, 1.0, v39
	v_rcp_f32_e32 v37, v37
	v_cmp_lt_i32_e32 vcc, 10, v127
	v_mul_f32_e32 v34, v128, v34
	v_cndmask_b32_e32 v138, 1.0, v36, vcc
	v_cndmask_b32_e32 v139, 0, v34, vcc
	v_mul_f32_e32 v34, v39, v37
	v_cmp_lt_i32_e32 vcc, 11, v127
	v_min_f32_e64 v36, -v40, s60
	v_exp_f32_e32 v36, v36
	v_cndmask_b32_e32 v39, 1.0, v34, vcc
	v_mul_f32_e32 v34, v128, v37
	v_min_f32_e64 v37, -v41, s60
	v_exp_f32_e32 v37, v37
	v_cndmask_b32_e32 v40, 0, v34, vcc
	v_add_f32_e32 v34, 1.0, v36
	v_rcp_f32_e32 v34, v34
	v_add_f32_e32 v41, 1.0, v37
	v_min_f32_e64 v42, -v42, s60
	v_rcp_f32_e32 v41, v41
	v_exp_f32_e32 v42, v42
	v_mul_f32_e32 v36, v36, v34
	v_cmp_lt_i32_e32 vcc, 16, v127
	v_mul_f32_e32 v34, v128, v34
	v_cndmask_b32_e32 v140, 0, v34, vcc
	v_mul_f32_e32 v34, v37, v41
	v_add_f32_e32 v37, 1.0, v42
	v_rcp_f32_e32 v37, v37
	v_cndmask_b32_e32 v36, 1.0, v36, vcc
	v_cmp_lt_i32_e32 vcc, 17, v127
	v_min_f32_e64 v45, -v45, s60
	v_cndmask_b32_e32 v141, 1.0, v34, vcc
	v_mul_f32_e32 v34, v128, v41
	v_cndmask_b32_e32 v41, 0, v34, vcc
	v_mul_f32_e32 v34, v42, v37
	v_cmp_lt_i32_e32 vcc, 18, v127
	v_min_f32_e64 v42, -v43, s60
	v_exp_f32_e32 v42, v42
	v_cndmask_b32_e32 v43, 1.0, v34, vcc
	v_mul_f32_e32 v34, v128, v37
	v_min_f32_e64 v37, -v44, s60
	v_exp_f32_e32 v37, v37
	v_cndmask_b32_e32 v142, 0, v34, vcc
	v_add_f32_e32 v34, 1.0, v42
	v_rcp_f32_e32 v34, v34
	v_add_f32_e32 v44, 1.0, v37
	v_rcp_f32_e32 v44, v44
	v_exp_f32_e32 v45, v45
	v_min_f32_e64 v46, -v46, s60
	v_min_f32_e64 v47, -v47, s60
	v_exp_f32_e32 v46, v46
	v_exp_f32_e32 v47, v47
	v_mul_f32_e32 v42, v42, v34
	v_cmp_lt_i32_e32 vcc, 19, v127
	v_mul_f32_e32 v34, v128, v34
	v_add_f32_e32 v130, 1.0, v46
	v_cndmask_b32_e32 v143, 0, v34, vcc
	v_mul_f32_e32 v34, v37, v44
	v_add_f32_e32 v37, 1.0, v45
	v_rcp_f32_e32 v37, v37
	v_add_f32_e32 v144, 1.0, v47
	v_rcp_f32_e32 v130, v130
	v_rcp_f32_e32 v144, v144
	v_cndmask_b32_e32 v42, 1.0, v42, vcc
	v_cmp_lt_i32_e32 vcc, 24, v127
	v_mul_f32_e32 v44, v128, v44
	v_mul_f32_e32 v45, v45, v37
	v_cndmask_b32_e32 v34, 1.0, v34, vcc
	v_cndmask_b32_e32 v44, 0, v44, vcc
	v_cmp_lt_i32_e32 vcc, 25, v127
	v_mul_f32_e32 v37, v128, v37
	v_mul_f32_e32 v46, v46, v130
	v_cndmask_b32_e32 v45, 1.0, v45, vcc
	v_cndmask_b32_e32 v37, 0, v37, vcc
	v_cmp_lt_i32_e32 vcc, 26, v127
	v_mul_f32_e32 v47, v47, v144
	v_cndmask_b32_e64 v47, 1.0, v47, s[0:1]
	v_cndmask_b32_e32 v46, 1.0, v46, vcc
	v_mul_f32_e32 v34, v34, v45
	v_mul_f32_e32 v127, v46, v47
	v_mul_f32_e32 v127, v34, v127
	v_mov_b32_e32 v145, v127
	v_mov_b32_e32 v240, v127
	s_nop 1
	v_permlane32_swap_b32_e32 v145, v240
	v_cndmask_b32_e64 v145, v145, v240, s[2:3]
	v_mul_f32_e32 v34, v128, v130
	v_cndmask_b32_e32 v130, 0, v34, vcc
	v_mul_f32_e32 v34, v128, v144
	v_cndmask_b32_e64 v34, 0, v34, s[0:1]
	s_waitcnt lgkmcnt(0)
	v_cndmask_b32_e64 v128, 1.0, v145, s[2:3]
	v_mul_f32_e32 v144, v34, v128
	v_mul_f32_e32 v34, v36, v141
	v_mul_f32_e32 v36, v43, v42
	v_mul_f32_e32 v36, v34, v36
	v_mul_f32_e32 v32, v32, v38
	v_mul_f32_e32 v34, v138, v39
	v_mov_b32_e32 v146, v36
	v_mov_b32_e32 v240, v36
	s_nop 1
	v_permlane32_swap_b32_e32 v146, v240
	v_cndmask_b32_e64 v146, v146, v240, s[2:3]
	v_mul_f32_e32 v34, v32, v34
	v_mul_f32_e32 v47, v47, v128
	v_mov_b32_e32 v128, v34
	v_mov_b32_e32 v240, v34
	s_nop 1
	v_permlane32_swap_b32_e32 v128, v240
	v_cndmask_b32_e64 v128, v128, v240, s[2:3]
	v_mul_f32_e32 v46, v46, v47
	v_mul_f32_e32 v47, v130, v47
	v_mul_f32_e32 v32, v127, v145
	s_waitcnt lgkmcnt(1)
	v_mul_f32_e32 v130, v36, v146
	v_mul_f32_e32 v45, v45, v46
	v_mul_f32_e32 v46, v37, v46
	s_waitcnt lgkmcnt(0)
	v_cndmask_b32_e64 v127, 1.0, v128, s[2:3]
	v_pk_mul_f32 v[36:37], v[32:33], v[130:131]
	v_pk_mul_f32 v[34:35], v[34:35], v[128:129]
	v_mul_f32_e32 v127, v36, v127
	v_mul_f32_e32 v130, v39, v127
	v_mul_f32_e32 v138, v138, v130
	v_mul_f32_e32 v145, v38, v138
	v_pk_mul_f32 v[38:39], v[34:35], v[36:37]
	v_mov_b32_e32 v128, v39
	v_mov_b32_e32 v240, v39
	s_nop 1
	v_permlane32_swap_b32_e32 v128, v240
	v_cndmask_b32_e64 v128, v128, v240, s[2:3]
	v_mul_f32_e32 v37, v40, v127
	v_mul_f32_e32 v40, v139, v130
	v_mul_f32_e32 v36, v137, v138
	v_mul_f32_e32 v127, v136, v145
	s_waitcnt lgkmcnt(0)
	v_cndmask_b32_e64 v34, 1.0, v128, s[2:3]
	v_mul_f32_e32 v34, v38, v34
	v_mul_f32_e32 v35, v131, v34
	v_mul_f32_e32 v33, v33, v35
	v_mul_f32_e32 v129, v129, v33
	v_mul_f32_e32 v130, v132, v34
	v_mul_f32_e32 v35, v135, v35
	v_mul_f32_e32 v33, v134, v33
	v_mul_f32_e32 v34, v133, v129
	v_cvt_pk_bf16_f32 v34, v34, v33
	v_cvt_pk_bf16_f32 v35, v35, v130
	v_cvt_pk_bf16_f32 v36, v127, v36
	v_cvt_pk_bf16_f32 v37, v40, v37
	v_cndmask_b32_e64 v33, 1.0, v146, s[2:3]
	v_mul_f32_e32 v32, v32, v33
	v_mfma_f32_32x32x16_bf16 v[16:31], v[92:95], v[34:37], v[16:31]
	v_mul_f32_e32 v33, v42, v32
	v_mul_f32_e32 v42, v43, v33
	v_mul_f32_e32 v43, v141, v42
	v_mul_f32_e32 v40, v44, v45
	v_mul_f32_e32 v44, v143, v32
	v_mul_f32_e32 v33, v142, v33
	v_mul_f32_e32 v32, v41, v42
	v_mfma_f32_32x32x16_bf16 v[0:15], v[88:91], v[34:37], v[0:15]
	v_mul_f32_e32 v34, v140, v43
	v_cvt_pk_bf16_f32 v32, v34, v32
	v_cvt_pk_bf16_f32 v33, v33, v44
	v_cvt_pk_bf16_f32 v34, v40, v46
	v_cvt_pk_bf16_f32 v35, v47, v144
	v_mul_f32_e32 v36, v39, v128
	v_mul_f32_e32 v36, v38, v36
	v_mfma_f32_32x32x16_bf16 v[16:31], v[84:87], v[32:35], v[16:31]
	v_log_f32_e32 v36, v36
	s_nop 0
	v_add_f32_e32 v125, v125, v36
	v_mfma_f32_32x32x16_bf16 v[0:15], v[80:83], v[32:35], v[0:15]
	s_branch .LBB0_349
.Lsbq0_nomask_2:
	ds_read_b128 v[32:35], v129
	ds_read_b128 v[214:217], v129 offset:32
	ds_read_b128 v[210:213], v129 offset:64
	ds_read_b128 v[130:133], v129 offset:96
	ds_read_b64_tr_b16 v[92:93], v128 offset:36864
	ds_read_b64_tr_b16 v[94:95], v128 offset:38400
	ds_read_b64_tr_b16 v[90:91], v128 offset:38464
	ds_read_b64_tr_b16 v[88:89], v128 offset:36928
	ds_read_b64_tr_b16 v[84:85], v128 offset:39936
	ds_read_b64_tr_b16 v[86:87], v128 offset:41472
	ds_read_b64_tr_b16 v[82:83], v128 offset:41536
	ds_read_b64_tr_b16 v[80:81], v128 offset:40000
	v_exp_f32_e32 v128, v125
	s_waitcnt lgkmcnt(11)
	v_mfma_f32_32x32x16_bf16 v[32:47], v[32:35], v[48:51], 0
	s_waitcnt lgkmcnt(10)
	v_mfma_f32_32x32x16_bf16 v[32:47], v[214:217], v[52:55], v[32:47]
	s_waitcnt lgkmcnt(9)
	v_mfma_f32_32x32x16_bf16 v[32:47], v[210:213], v[56:59], v[32:47]
	s_waitcnt lgkmcnt(8)
	v_mfma_f32_32x32x16_bf16 v[32:47], v[130:133], v[60:63], v[32:47]
	s_nop 11
	v_min_f32_e64 v32, -v32, s60
	v_min_f32_e64 v33, -v33, s60
	v_exp_f32_e32 v32, v32
	v_min_f32_e64 v34, -v34, s60
	v_exp_f32_e32 v33, v33
	v_exp_f32_e32 v34, v34
	v_min_f32_e64 v35, -v35, s60
	v_exp_f32_e32 v130, v35
	v_add_f32_e32 v35, 1.0, v32
	v_add_f32_e32 v129, 1.0, v33
	v_rcp_f32_e32 v35, v35
	v_add_f32_e32 v131, 1.0, v34
	v_rcp_f32_e32 v129, v129
	v_rcp_f32_e32 v131, v131
	v_add_f32_e32 v132, 1.0, v130
	v_rcp_f32_e32 v132, v132
	v_mul_f32_e32 v32, v32, v35
	v_mul_f32_e32 v133, v128, v35
	v_min_f32_e64 v36, -v36, s60
	v_mul_f32_e32 v33, v33, v129
	v_mul_f32_e32 v134, v128, v129
	v_mov_b32_e32 v35, v32
	v_mul_f32_e32 v34, v34, v131
	v_exp_f32_e32 v32, v36
	v_mov_b32_e32 v129, v33
	v_add_f32_e32 v36, 1.0, v32
	v_rcp_f32_e32 v36, v36
	v_mov_b32_e32 v33, v34
	v_mul_f32_e32 v135, v128, v131
	v_mul_f32_e32 v131, v130, v132
	v_mul_f32_e32 v32, v32, v36
	v_mul_f32_e32 v136, v128, v36
	v_mul_f32_e32 v132, v128, v132
	v_min_f32_e64 v34, -v37, s60
	v_exp_f32_e32 v34, v34
	v_min_f32_e64 v37, -v38, s60
	v_add_f32_e32 v36, 1.0, v34
	v_rcp_f32_e32 v36, v36
	v_exp_f32_e32 v37, v37
	v_mul_f32_e32 v38, v34, v36
	v_add_f32_e32 v34, 1.0, v37
	v_min_f32_e64 v39, -v39, s60
	v_rcp_f32_e32 v34, v34
	v_exp_f32_e32 v39, v39
	v_mul_f32_e32 v137, v128, v36
	v_mul_f32_e32 v138, v37, v34
	v_add_f32_e32 v37, 1.0, v39
	v_rcp_f32_e32 v37, v37
	v_mul_f32_e32 v139, v128, v34
	v_mul_f32_e32 v39, v39, v37
	v_min_f32_e64 v36, -v40, s60
	v_exp_f32_e32 v36, v36
	v_mul_f32_e32 v40, v128, v37
	v_min_f32_e64 v37, -v41, s60
	v_exp_f32_e32 v37, v37
	v_add_f32_e32 v34, 1.0, v36
	v_rcp_f32_e32 v34, v34
	v_add_f32_e32 v41, 1.0, v37
	v_min_f32_e64 v42, -v42, s60
	v_rcp_f32_e32 v41, v41
	v_exp_f32_e32 v42, v42
	v_mul_f32_e32 v36, v36, v34
	v_mul_f32_e32 v140, v128, v34
	v_mul_f32_e32 v141, v37, v41
	v_add_f32_e32 v37, 1.0, v42
	v_rcp_f32_e32 v37, v37
	v_min_f32_e64 v45, -v45, s60
	v_mul_f32_e32 v41, v128, v41
	v_mul_f32_e32 v34, v42, v37
	v_min_f32_e64 v42, -v43, s60
	v_exp_f32_e32 v42, v42
	v_mov_b32_e32 v43, v34
	v_mul_f32_e32 v142, v128, v37
	v_min_f32_e64 v37, -v44, s60
	v_exp_f32_e32 v37, v37
	v_add_f32_e32 v34, 1.0, v42
	v_rcp_f32_e32 v34, v34
	v_add_f32_e32 v44, 1.0, v37
	v_rcp_f32_e32 v44, v44
	v_exp_f32_e32 v45, v45
	v_min_f32_e64 v46, -v46, s60
	v_min_f32_e64 v47, -v47, s60
	v_exp_f32_e32 v46, v46
	v_exp_f32_e32 v47, v47
	v_mul_f32_e32 v42, v42, v34
	v_mul_f32_e32 v143, v128, v34
	v_add_f32_e32 v130, 1.0, v46
	v_mul_f32_e32 v34, v37, v44
	v_add_f32_e32 v37, 1.0, v45
	v_rcp_f32_e32 v37, v37
	v_add_f32_e32 v144, 1.0, v47
	v_rcp_f32_e32 v130, v130
	v_rcp_f32_e32 v144, v144
	v_mul_f32_e32 v44, v128, v44
	v_mul_f32_e32 v45, v45, v37
	v_mul_f32_e32 v37, v128, v37
	v_mul_f32_e32 v46, v46, v130
	v_mul_f32_e32 v47, v47, v144
	v_mul_f32_e32 v34, v34, v45
	v_mul_f32_e32 v127, v46, v47
	v_mul_f32_e32 v127, v34, v127
	v_mov_b32_e32 v145, v127
	v_mov_b32_e32 v240, v127
	s_nop 1
	v_permlane32_swap_b32_e32 v145, v240
	v_cndmask_b32_e64 v145, v145, v240, s[2:3]
	v_mul_f32_e32 v130, v128, v130
	v_mul_f32_e32 v34, v128, v144
	s_waitcnt lgkmcnt(0)
	v_cndmask_b32_e64 v128, 1.0, v145, s[2:3]
	v_mul_f32_e32 v144, v34, v128
	v_mul_f32_e32 v34, v36, v141
	v_mul_f32_e32 v36, v43, v42
	v_mul_f32_e32 v36, v34, v36
	v_mul_f32_e32 v32, v32, v38
	v_mul_f32_e32 v34, v138, v39
	v_mov_b32_e32 v146, v36
	v_mov_b32_e32 v240, v36
	s_nop 1
	v_permlane32_swap_b32_e32 v146, v240
	v_cndmask_b32_e64 v146, v146, v240, s[2:3]
	v_mul_f32_e32 v34, v32, v34
	v_mul_f32_e32 v47, v47, v128
	v_mov_b32_e32 v128, v34
	v_mov_b32_e32 v240, v34
	s_nop 1
	v_permlane32_swap_b32_e32 v128, v240
	v_cndmask_b32_e64 v128, v128, v240, s[2:3]
	v_mul_f32_e32 v46, v46, v47
	v_mul_f32_e32 v47, v130, v47
	v_mul_f32_e32 v32, v127, v145
	s_waitcnt lgkmcnt(1)
	v_mul_f32_e32 v130, v36, v146
	v_mul_f32_e32 v45, v45, v46
	v_mul_f32_e32 v46, v37, v46
	s_waitcnt lgkmcnt(0)
	v_cndmask_b32_e64 v127, 1.0, v128, s[2:3]
	v_pk_mul_f32 v[36:37], v[32:33], v[130:131]
	v_pk_mul_f32 v[34:35], v[34:35], v[128:129]
	v_mul_f32_e32 v127, v36, v127
	v_mul_f32_e32 v130, v39, v127
	v_mul_f32_e32 v138, v138, v130
	v_mul_f32_e32 v145, v38, v138
	v_pk_mul_f32 v[38:39], v[34:35], v[36:37]
	v_mov_b32_e32 v128, v39
	v_mov_b32_e32 v240, v39
	s_nop 1
	v_permlane32_swap_b32_e32 v128, v240
	v_cndmask_b32_e64 v128, v128, v240, s[2:3]
	v_mul_f32_e32 v37, v40, v127
	v_mul_f32_e32 v40, v139, v130
	v_mul_f32_e32 v36, v137, v138
	v_mul_f32_e32 v127, v136, v145
	s_waitcnt lgkmcnt(0)
	v_cndmask_b32_e64 v34, 1.0, v128, s[2:3]
	v_mul_f32_e32 v34, v38, v34
	v_mul_f32_e32 v35, v131, v34
	v_mul_f32_e32 v33, v33, v35
	v_mul_f32_e32 v129, v129, v33
	v_mul_f32_e32 v130, v132, v34
	v_mul_f32_e32 v35, v135, v35
	v_mul_f32_e32 v33, v134, v33
	v_mul_f32_e32 v34, v133, v129
	v_cvt_pk_bf16_f32 v34, v34, v33
	v_cvt_pk_bf16_f32 v35, v35, v130
	v_cvt_pk_bf16_f32 v36, v127, v36
	v_cvt_pk_bf16_f32 v37, v40, v37
	v_cndmask_b32_e64 v33, 1.0, v146, s[2:3]
	v_mul_f32_e32 v32, v32, v33
	v_mfma_f32_32x32x16_bf16 v[16:31], v[92:95], v[34:37], v[16:31]
	v_mul_f32_e32 v33, v42, v32
	v_mul_f32_e32 v42, v43, v33
	v_mul_f32_e32 v43, v141, v42
	v_mul_f32_e32 v40, v44, v45
	v_mul_f32_e32 v44, v143, v32
	v_mul_f32_e32 v33, v142, v33
	v_mul_f32_e32 v32, v41, v42
	v_mfma_f32_32x32x16_bf16 v[0:15], v[88:91], v[34:37], v[0:15]
	v_mul_f32_e32 v34, v140, v43
	v_cvt_pk_bf16_f32 v32, v34, v32
	v_cvt_pk_bf16_f32 v33, v33, v44
	v_cvt_pk_bf16_f32 v34, v40, v46
	v_cvt_pk_bf16_f32 v35, v47, v144
	v_mul_f32_e32 v36, v39, v128
	v_mul_f32_e32 v36, v38, v36
	v_mfma_f32_32x32x16_bf16 v[16:31], v[84:87], v[32:35], v[16:31]
	v_log_f32_e32 v36, v36
	s_nop 0
	v_add_f32_e32 v125, v125, v36
	v_mfma_f32_32x32x16_bf16 v[0:15], v[80:83], v[32:35], v[0:15]

; __device__ __forceinline__ void sb_unit(const Frame& F, int b, int hd, int qi, int dry) {
;     ...
;             float run = C;
;             if (!meta && key0 + 96 < tqw + 31) SB_HALF(96);
;             if (!meta && key0 + 64 < tqw + 31 && __any(run >= SB_DEAD)) SB_HALF(64);
;             if (!meta && key0 + 32 < tqw + 31 && __any(run >= SB_DEAD)) SB_HALF(32);
;             if (__any(run >= SB_DEAD)) SB_HALF(0);
.LBB0_370:
	v_cmp_le_f32_e32 vcc, s22, v126
	s_cbranch_vccz .LBB0_372
	s_and_b64 vcc, exec, s[18:19]
	s_cbranch_vccnz .Lsbq0_masked_1
	s_add_i32 s61, s34, 32
	s_cmp_le_i32 s61, s25
	s_cbranch_scc1 .Lsbq0_nomask_1
.Lsbq0_masked_1:
	ds_read_b128 v[32:35], v129
	ds_read_b128 v[214:217], v129 offset:32
	ds_read_b128 v[210:213], v129 offset:64
	ds_read_b128 v[130:133], v129 offset:96
	ds_read_b64_tr_b16 v[92:93], v128 offset:36864
	ds_read_b64_tr_b16 v[94:95], v128 offset:38400
	ds_read_b64_tr_b16 v[90:91], v128 offset:38464
	ds_read_b64_tr_b16 v[88:89], v128 offset:36928
	ds_read_b64_tr_b16 v[84:85], v128 offset:39936
	ds_read_b64_tr_b16 v[86:87], v128 offset:41472
	ds_read_b64_tr_b16 v[82:83], v128 offset:41536
	ds_read_b64_tr_b16 v[80:81], v128 offset:40000
	v_cndmask_b32_e64 v129, v114, 16, s[18:19]
	v_sub_u32_e32 v127, v129, v127
	v_cmp_lt_i32_e32 vcc, 0, v127
	v_cmp_lt_i32_e64 s[0:1], 27, v127
	v_exp_f32_e32 v128, v126
	s_waitcnt lgkmcnt(11)
	v_mfma_f32_32x32x16_bf16 v[32:47], v[32:35], v[48:51], 0
	s_waitcnt lgkmcnt(10)
	v_mfma_f32_32x32x16_bf16 v[32:47], v[214:217], v[52:55], v[32:47]
	s_waitcnt lgkmcnt(9)
	v_mfma_f32_32x32x16_bf16 v[32:47], v[210:213], v[56:59], v[32:47]
	s_waitcnt lgkmcnt(8)
	v_mfma_f32_32x32x16_bf16 v[32:47], v[130:133], v[60:63], v[32:47]
	s_nop 11
	v_min_f32_e64 v32, -v32, s60
	v_min_f32_e64 v33, -v33, s60
	v_exp_f32_e32 v32, v32
	v_min_f32_e64 v34, -v34, s60
	v_exp_f32_e32 v33, v33
	v_exp_f32_e32 v34, v34
	v_min_f32_e64 v35, -v35, s60
	v_exp_f32_e32 v130, v35
	v_add_f32_e32 v35, 1.0, v32
	v_add_f32_e32 v129, 1.0, v33
	v_rcp_f32_e32 v35, v35
	v_add_f32_e32 v131, 1.0, v34
	v_rcp_f32_e32 v129, v129
	v_rcp_f32_e32 v131, v131
	v_add_f32_e32 v132, 1.0, v130
	v_rcp_f32_e32 v132, v132
	v_mul_f32_e32 v32, v32, v35
	v_mul_f32_e32 v133, v128, v35
	v_min_f32_e64 v36, -v36, s60
	v_mul_f32_e32 v33, v33, v129
	v_mul_f32_e32 v134, v128, v129
	v_cndmask_b32_e32 v35, 1.0, v32, vcc
	v_cndmask_b32_e32 v133, 0, v133, vcc
	v_cmp_lt_i32_e32 vcc, 1, v127
	v_mul_f32_e32 v34, v34, v131
	v_exp_f32_e32 v32, v36
	v_cndmask_b32_e32 v129, 1.0, v33, vcc
	v_cndmask_b32_e32 v134, 0, v134, vcc
	v_cmp_lt_i32_e32 vcc, 2, v127
	v_add_f32_e32 v36, 1.0, v32
	v_rcp_f32_e32 v36, v36
	v_cndmask_b32_e32 v33, 1.0, v34, vcc
	v_mul_f32_e32 v34, v128, v131
	v_cndmask_b32_e32 v135, 0, v34, vcc
	v_mul_f32_e32 v34, v130, v132
	v_cmp_lt_i32_e32 vcc, 3, v127
	v_mul_f32_e32 v32, v32, v36
	v_mul_f32_e32 v36, v128, v36
	v_cndmask_b32_e32 v131, 1.0, v34, vcc
	v_mul_f32_e32 v34, v128, v132
	v_cndmask_b32_e32 v132, 0, v34, vcc
	v_min_f32_e64 v34, -v37, s60
	v_exp_f32_e32 v34, v34
	v_cmp_lt_i32_e32 vcc, 8, v127
	v_min_f32_e64 v37, -v38, s60
	v_cndmask_b32_e32 v136, 0, v36, vcc
	v_add_f32_e32 v36, 1.0, v34
	v_rcp_f32_e32 v36, v36
	v_exp_f32_e32 v37, v37
	v_cndmask_b32_e32 v32, 1.0, v32, vcc
	v_cmp_lt_i32_e32 vcc, 9, v127
	v_mul_f32_e32 v34, v34, v36
	v_cndmask_b32_e32 v38, 1.0, v34, vcc
	v_add_f32_e32 v34, 1.0, v37
	v_min_f32_e64 v39, -v39, s60
	v_rcp_f32_e32 v34, v34
	v_exp_f32_e32 v39, v39
	v_mul_f32_e32 v36, v128, v36
	v_cndmask_b32_e32 v137, 0, v36, vcc
	v_mul_f32_e32 v36, v37, v34
	v_add_f32_e32 v37, 1.0, v39
	v_rcp_f32_e32 v37, v37
	v_cmp_lt_i32_e32 vcc, 10, v127
	v_mul_f32_e32 v34, v128, v34
	v_cndmask_b32_e32 v138, 1.0, v36, vcc
	v_cndmask_b32_e32 v139, 0, v34, vcc
	v_mul_f32_e32 v34, v39, v37
	v_cmp_lt_i32_e32 vcc, 11, v127
	v_min_f32_e64 v36, -v40, s60
	v_exp_f32_e32 v36, v36
	v_cndmask_b32_e32 v39, 1.0, v34, vcc
	v_mul_f32_e32 v34, v128, v37
	v_min_f32_e64 v37, -v41, s60
	v_exp_f32_e32 v37, v37
	v_cndmask_b32_e32 v40, 0, v34, vcc
	v_add_f32_e32 v34, 1.0, v36
	v_rcp_f32_e32 v34, v34
	v_add_f32_e32 v41, 1.0, v37
	v_min_f32_e64 v42, -v42, s60
	v_rcp_f32_e32 v41, v41
	v_exp_f32_e32 v42, v42
	v_mul_f32_e32 v36, v36, v34
	v_cmp_lt_i32_e32 vcc, 16, v127
	v_mul_f32_e32 v34, v128, v34
	v_cndmask_b32_e32 v140, 0, v34, vcc
	v_mul_f32_e32 v34, v37, v41
	v_add_f32_e32 v37, 1.0, v42
	v_rcp_f32_e32 v37, v37
	v_cndmask_b32_e32 v36, 1.0, v36, vcc
	v_cmp_lt_i32_e32 vcc, 17, v127
	v_min_f32_e64 v45, -v45, s60
	v_cndmask_b32_e32 v141, 1.0, v34, vcc
	v_mul_f32_e32 v34, v128, v41
	v_cndmask_b32_e32 v41, 0, v34, vcc
	v_mul_f32_e32 v34, v42, v37
	v_cmp_lt_i32_e32 vcc, 18, v127
	v_min_f32_e64 v42, -v43, s60
	v_exp_f32_e32 v42, v42
	v_cndmask_b32_e32 v43, 1.0, v34, vcc
	v_mul_f32_e32 v34, v128, v37
	v_min_f32_e64 v37, -v44, s60
	v_exp_f32_e32 v37, v37
	v_cndmask_b32_e32 v142, 0, v34, vcc
	v_add_f32_e32 v34, 1.0, v42
	v_rcp_f32_e32 v34, v34
	v_add_f32_e32 v44, 1.0, v37
	v_rcp_f32_e32 v44, v44
	v_exp_f32_e32 v45, v45
	v_min_f32_e64 v46, -v46, s60
	v_min_f32_e64 v47, -v47, s60
	v_exp_f32_e32 v46, v46
	v_exp_f32_e32 v47, v47
	v_mul_f32_e32 v42, v42, v34
	v_cmp_lt_i32_e32 vcc, 19, v127
	v_mul_f32_e32 v34, v128, v34
	v_add_f32_e32 v130, 1.0, v46
	v_cndmask_b32_e32 v143, 0, v34, vcc
	v_mul_f32_e32 v34, v37, v44
	v_add_f32_e32 v37, 1.0, v45
	v_rcp_f32_e32 v37, v37
	v_add_f32_e32 v144, 1.0, v47
	v_rcp_f32_e32 v130, v130
	v_rcp_f32_e32 v144, v144
	v_cndmask_b32_e32 v42, 1.0, v42, vcc
	v_cmp_lt_i32_e32 vcc, 24, v127
	v_mul_f32_e32 v44, v128, v44
	v_mul_f32_e32 v45, v45, v37
	v_cndmask_b32_e32 v34, 1.0, v34, vcc
	v_cndmask_b32_e32 v44, 0, v44, vcc
	v_cmp_lt_i32_e32 vcc, 25, v127
	v_mul_f32_e32 v37, v128, v37
	v_mul_f32_e32 v46, v46, v130
	v_cndmask_b32_e32 v45, 1.0, v45, vcc
	v_cndmask_b32_e32 v37, 0, v37, vcc
	v_cmp_lt_i32_e32 vcc, 26, v127
	v_mul_f32_e32 v47, v47, v144
	v_cndmask_b32_e64 v47, 1.0, v47, s[0:1]
	v_cndmask_b32_e32 v46, 1.0, v46, vcc
	v_mul_f32_e32 v34, v34, v45
	v_mul_f32_e32 v127, v46, v47
	v_mul_f32_e32 v127, v34, v127
	v_mov_b32_e32 v145, v127
	v_mov_b32_e32 v240, v127
	s_nop 1
	v_permlane32_swap_b32_e32 v145, v240
	v_cndmask_b32_e64 v145, v145, v240, s[2:3]
	v_mul_f32_e32 v34, v128, v130
	v_cndmask_b32_e32 v130, 0, v34, vcc
	v_mul_f32_e32 v34, v128, v144
	v_cndmask_b32_e64 v34, 0, v34, s[0:1]
	s_waitcnt lgkmcnt(0)
	v_cndmask_b32_e64 v128, 1.0, v145, s[2:3]
	v_mul_f32_e32 v144, v34, v128
	v_mul_f32_e32 v34, v36, v141
	v_mul_f32_e32 v36, v43, v42
	v_mul_f32_e32 v36, v34, v36
	v_mul_f32_e32 v32, v32, v38
	v_mul_f32_e32 v34, v138, v39
	v_mov_b32_e32 v146, v36
	v_mov_b32_e32 v240, v36
	s_nop 1
	v_permlane32_swap_b32_e32 v146, v240
	v_cndmask_b32_e64 v146, v146, v240, s[2:3]
	v_mul_f32_e32 v34, v32, v34
	v_mul_f32_e32 v47, v47, v128
	v_mov_b32_e32 v128, v34
	v_mov_b32_e32 v240, v34
	s_nop 1
	v_permlane32_swap_b32_e32 v128, v240
	v_cndmask_b32_e64 v128, v128, v240, s[2:3]
	v_mul_f32_e32 v46, v46, v47
	v_mul_f32_e32 v47, v130, v47
	v_mul_f32_e32 v32, v127, v145
	s_waitcnt lgkmcnt(1)
	v_mul_f32_e32 v130, v36, v146
	v_mul_f32_e32 v45, v45, v46
	v_mul_f32_e32 v46, v37, v46
	s_waitcnt lgkmcnt(0)
	v_cndmask_b32_e64 v127, 1.0, v128, s[2:3]
	v_pk_mul_f32 v[36:37], v[32:33], v[130:131]
	v_pk_mul_f32 v[34:35], v[34:35], v[128:129]
	v_mul_f32_e32 v127, v36, v127
	v_mul_f32_e32 v130, v39, v127
	v_mul_f32_e32 v138, v138, v130
	v_mul_f32_e32 v145, v38, v138
	v_pk_mul_f32 v[38:39], v[34:35], v[36:37]
	v_mov_b32_e32 v128, v39
	v_mov_b32_e32 v240, v39
	s_nop 1
	v_permlane32_swap_b32_e32 v128, v240
	v_cndmask_b32_e64 v128, v128, v240, s[2:3]
	v_mul_f32_e32 v37, v40, v127
	v_mul_f32_e32 v40, v139, v130
	v_mul_f32_e32 v36, v137, v138
	v_mul_f32_e32 v127, v136, v145
	s_waitcnt lgkmcnt(0)
	v_cndmask_b32_e64 v34, 1.0, v128, s[2:3]
	v_mul_f32_e32 v34, v38, v34
	v_mul_f32_e32 v35, v131, v34
	v_mul_f32_e32 v33, v33, v35
	v_mul_f32_e32 v129, v129, v33
	v_mul_f32_e32 v130, v132, v34
	v_mul_f32_e32 v35, v135, v35
	v_mul_f32_e32 v33, v134, v33
	v_mul_f32_e32 v34, v133, v129
	v_cvt_pk_bf16_f32 v34, v34, v33
	v_cvt_pk_bf16_f32 v35, v35, v130
	v_cvt_pk_bf16_f32 v36, v127, v36
	v_cvt_pk_bf16_f32 v37, v40, v37
	v_cndmask_b32_e64 v33, 1.0, v146, s[2:3]
	v_mul_f32_e32 v32, v32, v33
	v_mfma_f32_32x32x16_bf16 v[0:15], v[92:95], v[34:37], v[0:15]
	v_mul_f32_e32 v33, v42, v32
	v_mul_f32_e32 v42, v43, v33
	v_mul_f32_e32 v43, v141, v42
	v_mul_f32_e32 v40, v44, v45
	v_mul_f32_e32 v44, v143, v32
	v_mul_f32_e32 v33, v142, v33
	v_mul_f32_e32 v32, v41, v42
	v_mfma_f32_32x32x16_bf16 v[16:31], v[88:91], v[34:37], v[16:31]
	v_mul_f32_e32 v34, v140, v43
	v_cvt_pk_bf16_f32 v32, v34, v32
	v_cvt_pk_bf16_f32 v33, v33, v44
	v_cvt_pk_bf16_f32 v34, v40, v46
	v_cvt_pk_bf16_f32 v35, v47, v144
	v_mul_f32_e32 v36, v39, v128
	v_mul_f32_e32 v36, v38, v36
	v_mfma_f32_32x32x16_bf16 v[0:15], v[84:87], v[32:35], v[0:15]
	v_log_f32_e32 v36, v36
	s_nop 0
	v_add_f32_e32 v126, v126, v36
	v_mfma_f32_32x32x16_bf16 v[16:31], v[80:83], v[32:35], v[16:31]
	s_branch .LBB0_372
.Lsbq0_nomask_1:
	ds_read_b128 v[32:35], v129
	ds_read_b128 v[214:217], v129 offset:32
	ds_read_b128 v[210:213], v129 offset:64
	ds_read_b128 v[130:133], v129 offset:96
	ds_read_b64_tr_b16 v[92:93], v128 offset:36864
	ds_read_b64_tr_b16 v[94:95], v128 offset:38400
	ds_read_b64_tr_b16 v[90:91], v128 offset:38464
	ds_read_b64_tr_b16 v[88:89], v128 offset:36928
	ds_read_b64_tr_b16 v[84:85], v128 offset:39936
	ds_read_b64_tr_b16 v[86:87], v128 offset:41472
	ds_read_b64_tr_b16 v[82:83], v128 offset:41536
	ds_read_b64_tr_b16 v[80:81], v128 offset:40000
	v_exp_f32_e32 v128, v126
	s_waitcnt lgkmcnt(11)
	v_mfma_f32_32x32x16_bf16 v[32:47], v[32:35], v[48:51], 0
	s_waitcnt lgkmcnt(10)
	v_mfma_f32_32x32x16_bf16 v[32:47], v[214:217], v[52:55], v[32:47]
	s_waitcnt lgkmcnt(9)
	v_mfma_f32_32x32x16_bf16 v[32:47], v[210:213], v[56:59], v[32:47]
	s_waitcnt lgkmcnt(8)
	v_mfma_f32_32x32x16_bf16 v[32:47], v[130:133], v[60:63], v[32:47]
	s_nop 11
	v_min_f32_e64 v32, -v32, s60
	v_min_f32_e64 v33, -v33, s60
	v_exp_f32_e32 v32, v32
	v_min_f32_e64 v34, -v34, s60
	v_exp_f32_e32 v33, v33
	v_exp_f32_e32 v34, v34
	v_min_f32_e64 v35, -v35, s60
	v_exp_f32_e32 v130, v35
	v_add_f32_e32 v35, 1.0, v32
	v_add_f32_e32 v129, 1.0, v33
	v_rcp_f32_e32 v35, v35
	v_add_f32_e32 v131, 1.0, v34
	v_rcp_f32_e32 v129, v129
	v_rcp_f32_e32 v131, v131
	v_add_f32_e32 v132, 1.0, v130
	v_rcp_f32_e32 v132, v132
	v_mul_f32_e32 v32, v32, v35
	v_mul_f32_e32 v133, v128, v35
	v_min_f32_e64 v36, -v36, s60
	v_mul_f32_e32 v33, v33, v129
	v_mul_f32_e32 v134, v128, v129
	v_mov_b32_e32 v35, v32
	v_mul_f32_e32 v34, v34, v131
	v_exp_f32_e32 v32, v36
	v_mov_b32_e32 v129, v33
	v_add_f32_e32 v36, 1.0, v32
	v_rcp_f32_e32 v36, v36
	v_mov_b32_e32 v33, v34
	v_mul_f32_e32 v135, v128, v131
	v_mul_f32_e32 v131, v130, v132
	v_mul_f32_e32 v32, v32, v36
	v_mul_f32_e32 v136, v128, v36
	v_mul_f32_e32 v132, v128, v132
	v_min_f32_e64 v34, -v37, s60
	v_exp_f32_e32 v34, v34
	v_min_f32_e64 v37, -v38, s60
	v_add_f32_e32 v36, 1.0, v34
	v_rcp_f32_e32 v36, v36
	v_exp_f32_e32 v37, v37
	v_mul_f32_e32 v38, v34, v36
	v_add_f32_e32 v34, 1.0, v37
	v_min_f32_e64 v39, -v39, s60
	v_rcp_f32_e32 v34, v34
	v_exp_f32_e32 v39, v39
	v_mul_f32_e32 v137, v128, v36
	v_mul_f32_e32 v138, v37, v34
	v_add_f32_e32 v37, 1.0, v39
	v_rcp_f32_e32 v37, v37
	v_mul_f32_e32 v139, v128, v34
	v_mul_f32_e32 v39, v39, v37
	v_min_f32_e64 v36, -v40, s60
	v_exp_f32_e32 v36, v36
	v_mul_f32_e32 v40, v128, v37
	v_min_f32_e64 v37, -v41, s60
	v_exp_f32_e32 v37, v37
	v_add_f32_e32 v34, 1.0, v36
	v_rcp_f32_e32 v34, v34
	v_add_f32_e32 v41, 1.0, v37
	v_min_f32_e64 v42, -v42, s60
	v_rcp_f32_e32 v41, v41
	v_exp_f32_e32 v42, v42
	v_mul_f32_e32 v36, v36, v34
	v_mul_f32_e32 v140, v128, v34
	v_mul_f32_e32 v141, v37, v41
	v_add_f32_e32 v37, 1.0, v42
	v_rcp_f32_e32 v37, v37
	v_min_f32_e64 v45, -v45, s60
	v_mul_f32_e32 v41, v128, v41
	v_mul_f32_e32 v34, v42, v37
	v_min_f32_e64 v42, -v43, s60
	v_exp_f32_e32 v42, v42
	v_mov_b32_e32 v43, v34
	v_mul_f32_e32 v142, v128, v37
	v_min_f32_e64 v37, -v44, s60
	v_exp_f32_e32 v37, v37
	v_add_f32_e32 v34, 1.0, v42
	v_rcp_f32_e32 v34, v34
	v_add_f32_e32 v44, 1.0, v37
	v_rcp_f32_e32 v44, v44
	v_exp_f32_e32 v45, v45
	v_min_f32_e64 v46, -v46, s60
	v_min_f32_e64 v47, -v47, s60
	v_exp_f32_e32 v46, v46
	v_exp_f32_e32 v47, v47
	v_mul_f32_e32 v42, v42, v34
	v_mul_f32_e32 v143, v128, v34
	v_add_f32_e32 v130, 1.0, v46
	v_mul_f32_e32 v34, v37, v44
	v_add_f32_e32 v37, 1.0, v45
	v_rcp_f32_e32 v37, v37
	v_add_f32_e32 v144, 1.0, v47
	v_rcp_f32_e32 v130, v130
	v_rcp_f32_e32 v144, v144
	v_mul_f32_e32 v44, v128, v44
	v_mul_f32_e32 v45, v45, v37
	v_mul_f32_e32 v37, v128, v37
	v_mul_f32_e32 v46, v46, v130
	v_mul_f32_e32 v47, v47, v144
	v_mul_f32_e32 v34, v34, v45
	v_mul_f32_e32 v127, v46, v47
	v_mul_f32_e32 v127, v34, v127
	v_mov_b32_e32 v145, v127
	v_mov_b32_e32 v240, v127
	s_nop 1
	v_permlane32_swap_b32_e32 v145, v240
	v_cndmask_b32_e64 v145, v145, v240, s[2:3]
	v_mul_f32_e32 v130, v128, v130
	v_mul_f32_e32 v34, v128, v144
	s_waitcnt lgkmcnt(0)
	v_cndmask_b32_e64 v128, 1.0, v145, s[2:3]
	v_mul_f32_e32 v144, v34, v128
	v_mul_f32_e32 v34, v36, v141
	v_mul_f32_e32 v36, v43, v42
	v_mul_f32_e32 v36, v34, v36
	v_mul_f32_e32 v32, v32, v38
	v_mul_f32_e32 v34, v138, v39
	v_mov_b32_e32 v146, v36
	v_mov_b32_e32 v240, v36
	s_nop 1
	v_permlane32_swap_b32_e32 v146, v240
	v_cndmask_b32_e64 v146, v146, v240, s[2:3]
	v_mul_f32_e32 v34, v32, v34
	v_mul_f32_e32 v47, v47, v128
	v_mov_b32_e32 v128, v34
	v_mov_b32_e32 v240, v34
	s_nop 1
	v_permlane32_swap_b32_e32 v128, v240
	v_cndmask_b32_e64 v128, v128, v240, s[2:3]
	v_mul_f32_e32 v46, v46, v47
	v_mul_f32_e32 v47, v130, v47
	v_mul_f32_e32 v32, v127, v145
	s_waitcnt lgkmcnt(1)
	v_mul_f32_e32 v130, v36, v146
	v_mul_f32_e32 v45, v45, v46
	v_mul_f32_e32 v46, v37, v46
	s_waitcnt lgkmcnt(0)
	v_cndmask_b32_e64 v127, 1.0, v128, s[2:3]
	v_pk_mul_f32 v[36:37], v[32:33], v[130:131]
	v_pk_mul_f32 v[34:35], v[34:35], v[128:129]
	v_mul_f32_e32 v127, v36, v127
	v_mul_f32_e32 v130, v39, v127
	v_mul_f32_e32 v138, v138, v130
	v_mul_f32_e32 v145, v38, v138
	v_pk_mul_f32 v[38:39], v[34:35], v[36:37]
	v_mov_b32_e32 v128, v39
	v_mov_b32_e32 v240, v39
	s_nop 1
	v_permlane32_swap_b32_e32 v128, v240
	v_cndmask_b32_e64 v128, v128, v240, s[2:3]
	v_mul_f32_e32 v37, v40, v127
	v_mul_f32_e32 v40, v139, v130
	v_mul_f32_e32 v36, v137, v138
	v_mul_f32_e32 v127, v136, v145
	s_waitcnt lgkmcnt(0)
	v_cndmask_b32_e64 v34, 1.0, v128, s[2:3]
	v_mul_f32_e32 v34, v38, v34
	v_mul_f32_e32 v35, v131, v34
	v_mul_f32_e32 v33, v33, v35
	v_mul_f32_e32 v129, v129, v33
	v_mul_f32_e32 v130, v132, v34
	v_mul_f32_e32 v35, v135, v35
	v_mul_f32_e32 v33, v134, v33
	v_mul_f32_e32 v34, v133, v129
	v_cvt_pk_bf16_f32 v34, v34, v33
	v_cvt_pk_bf16_f32 v35, v35, v130
	v_cvt_pk_bf16_f32 v36, v127, v36
	v_cvt_pk_bf16_f32 v37, v40, v37
	v_cndmask_b32_e64 v33, 1.0, v146, s[2:3]
	v_mul_f32_e32 v32, v32, v33
	v_mfma_f32_32x32x16_bf16 v[0:15], v[92:95], v[34:37], v[0:15]
	v_mul_f32_e32 v33, v42, v32
	v_mul_f32_e32 v42, v43, v33
	v_mul_f32_e32 v43, v141, v42
	v_mul_f32_e32 v40, v44, v45
	v_mul_f32_e32 v44, v143, v32
	v_mul_f32_e32 v33, v142, v33
	v_mul_f32_e32 v32, v41, v42
	v_mfma_f32_32x32x16_bf16 v[16:31], v[88:91], v[34:37], v[16:31]
	v_mul_f32_e32 v34, v140, v43
	v_cvt_pk_bf16_f32 v32, v34, v32
	v_cvt_pk_bf16_f32 v33, v33, v44
	v_cvt_pk_bf16_f32 v34, v40, v46
	v_cvt_pk_bf16_f32 v35, v47, v144
	v_mul_f32_e32 v36, v39, v128
	v_mul_f32_e32 v36, v38, v36
	v_mfma_f32_32x32x16_bf16 v[0:15], v[84:87], v[32:35], v[0:15]
	v_log_f32_e32 v36, v36
	s_nop 0
	v_add_f32_e32 v126, v126, v36
	v_mfma_f32_32x32x16_bf16 v[16:31], v[80:83], v[32:35], v[16:31]
